# v_f1 + P7 A-piece remap: each wave's two A pieces cover adjacent row blocks (LDS layout unchanged)
# baseline (speedup 1.0000x reference)
.LBB0_1356:
	s_lshl_b32 s8, s0, 3
	s_sub_i32 s5, s5, s8
	s_lshl_b32 s4, s4, 3
	s_sext_i32_i8 s5, s5
	s_add_i32 s53, s4, s5
	s_mul_i32 s5, s53, 0x160000
	s_mul_hi_i32 s4, s53, 0x160000
	s_add_u32 s14, s66, s5
	s_addc_u32 s15, s67, s4
	v_and_b32_e32 v2, 15, v2
	s_movk_i32 s4, 0x70
	v_and_or_b32 v3, v3, s4, v2
	s_movk_i32 s4, 0xf0
	v_mul_u32_u24_e32 v3, 0xb00, v3
	v_and_or_b32 v2, v4, s4, v2
	v_or_b32_e32 v3, v1, v3
	v_mul_u32_u24_e32 v2, 0xb00, v2
	s_add_i32 s22, s1, 0x100
	s_lshr_b32 s79, s1, 10
	s_and_b32 s80, s79, 1
	s_lshr_b32 s79, s79, 1
	s_lshl_b32 s79, s79, 2
	s_add_i32 s80, s80, s79
	s_lshl_b32 s80, s80, 10
	s_add_i32 s70, s80, 0x100
	s_add_i32 s71, s70, 0x800
	s_add_i32 s72, s70, 0x4000
	s_add_i32 s73, s70, 0x4800
	s_add_i32 s74, s70, 0x8000
	s_add_i32 s75, s70, 0x8800
	s_add_i32 s76, s70, 0xc000
	s_add_i32 s77, s70, 0xc800
	s_movk_i32 s78, 0x1600
	s_lshr_b32 s8, s6, 8
	v_lshlrev_b32_e32 v170, 1, v3
	v_and_b32_e32 v170, 63, v170
	v_bfe_u32 v250, v184, 2, 4
	v_bfe_u32 v251, v184, 7, 2
	v_lshl_add_u32 v250, v251, 5, v250
	v_bfe_u32 v251, v184, 6, 1
	v_lshl_add_u32 v170, v251, 6, v170
	v_mad_u32_u24 v170, v250, s78, v170
	v_or_b32_e32 v1, v2, v1
	s_mov_b32 s1, m0
	s_mov_b32 m0, s70
	s_nop 0
	global_load_lds_dwordx4 v170, s[14:15]
	s_mov_b32 m0, s1
	s_add_i32 s23, s22, 0x2000
	v_lshlrev_b32_e32 v171, 1, v1
	v_add_u32_e32 v171, 0x16000, v170
	s_mov_b32 s1, m0
	s_mov_b32 m0, s71
	s_nop 0
	global_load_lds_dwordx4 v171, s[14:15]
	s_mov_b32 m0, s1
	s_add_u32 s10, s14, 0xb0000
	s_addc_u32 s11, s15, 0
	s_add_i32 s24, s22, 0x4000
	s_mov_b32 s1, m0
	s_mov_b32 m0, s72
	s_nop 0
	global_load_lds_dwordx4 v170, s[10:11]
	s_mov_b32 m0, s1
	s_add_i32 s25, s22, 0x6000
	s_mov_b32 s1, m0
	s_mov_b32 m0, s73
	s_nop 0
	global_load_lds_dwordx4 v171, s[10:11]
	s_mov_b32 m0, s1
	s_cmp_eq_u32 s8, 1
	s_cselect_b64 s[4:5], -1, 0
	s_cmp_lg_u32 s8, 1
	s_cbranch_scc1 .LBB0_1358
	s_barrier
.LBB0_1358:
	v_and_b32_e32 v1, 15, v184
	v_lshlrev_b32_e32 v2, 1, v0
	v_lshlrev_b32_e32 v3, 2, v184
	s_sext_i32_i8 s54, s0
	v_lshl_or_b32 v172, s8, 6, v1
	v_lshl_or_b32 v1, v1, 6, v2
	s_lshl_b32 s0, s8, 13
	v_and_b32_e32 v3, 32, v3
	v_bitop3_b32 v1, v1, s0, v3 bitop3:0xde
	s_lshl_b32 s0, s7, 5
	s_and_b32 s8, s0, 0x60
	v_lshlrev_b32_e32 v4, 6, v184
	s_movk_i32 s0, 0x3c0
	v_and_or_b32 v2, v4, s0, v2
	s_lshl_b32 s0, s8, 7
	v_bitop3_b32 v2, s0, v2, v3 bitop3:0xf6
	s_add_u32 s0, s12, 0x80
	s_waitcnt vmcnt(2)
	s_barrier
	s_addc_u32 s1, s13, 0
	s_add_i32 s27, s22, 0x18000
	s_mov_b32 s7, m0
	s_mov_b32 m0, s27
	s_nop 0
	global_load_lds_dwordx4 v168, s[0:1]
	s_mov_b32 m0, s7
	s_add_i32 s28, s22, 0x1a000
	s_mov_b32 s7, m0
	s_mov_b32 m0, s28
	s_nop 0
	global_load_lds_dwordx4 v169, s[0:1]
	s_mov_b32 m0, s7
	s_add_u32 s0, s14, 0x80
	s_addc_u32 s1, s15, 0
	s_add_i32 s29, s22, 0x8000
	s_mov_b32 s7, m0
	s_mov_b32 m0, s74
	s_nop 0
	global_load_lds_dwordx4 v170, s[0:1]
	s_mov_b32 m0, s7
	s_add_i32 s30, s22, 0xa000
	s_mov_b32 s7, m0
	s_mov_b32 m0, s75
	s_nop 0
	global_load_lds_dwordx4 v171, s[0:1]
	s_mov_b32 m0, s7
	s_add_u32 s0, s12, 0xb0080
	s_addc_u32 s1, s13, 0
	s_add_i32 s31, s22, 0x1c000
	s_mov_b32 s7, m0
	s_mov_b32 m0, s31
	s_nop 0
	global_load_lds_dwordx4 v168, s[0:1]
	s_mov_b32 m0, s7
	s_add_i32 s33, s22, 0x1e000
	s_mov_b32 s7, m0
	s_mov_b32 m0, s33
	s_nop 0
	global_load_lds_dwordx4 v169, s[0:1]
	s_mov_b32 m0, s7
	s_waitcnt vmcnt(6)
	s_add_i32 s34, s22, 0xc000
	s_add_i32 s36, s22, 0x10000
	s_add_i32 s37, s22, 0x14000
	s_cmpk_lt_u32 s6, 0x100
	v_or_b32_e32 v173, s8, v0
	v_add_u32_e32 v0, 0x100, v2
	s_mov_b32 s26, 0x18000
	s_mov_b32 s35, 0x10000
	s_cselect_b64 s[6:7], -1, 0
	s_add_i32 s38, s22, 0xe000
	s_add_i32 s39, s22, 0x12000
	s_add_i32 s40, s22, 0x16000
	s_add_i32 s41, s88, -2
	s_mov_b32 s0, 0
	v_add_u32_e32 v174, 0x10000, v0
	v_add_u32_e32 v175, 0x14000, v0
	v_add_u32_e32 v176, 0x100, v1
	v_add_u32_e32 v177, 0x18000, v0
	v_add_u32_e32 v178, 0x1c000, v0
	s_mov_b32 s42, 0x20000
	s_mov_b32 s43, 0x30000
	s_mov_b32 s46, 0x80000
	s_mov_b32 s47, 0x90000
	s_mov_b32 s48, 0xa0000
	s_mov_b32 s49, 0xb0000
	v_mov_b64_e32 v[164:165], 0x1ff
	s_barrier
	s_branch .LBB0_1361

.LBB0_1372:
	ds_read_b128 v[0:3], v174
	ds_read_b128 v[4:7], v174 offset:1024
	ds_read_b128 v[8:11], v174 offset:2048
	ds_read_b128 v[12:15], v174 offset:3072
	ds_read_b128 v[16:19], v175
	ds_read_b128 v[20:23], v175 offset:1024
	ds_read_b128 v[24:27], v175 offset:2048
	ds_read_b128 v[28:31], v175 offset:3072
	s_add_u32 s16, s14, 0x100
	s_addc_u32 s17, s15, 0
	s_add_u32 s18, s14, 0x180
	s_addc_u32 s19, s15, 0
	s_add_u32 s20, s12, 0x100
	s_addc_u32 s21, s13, 0
	ds_read_b128 v[32:35], v176
	ds_read_b128 v[36:39], v176 offset:1024
	ds_read_b128 v[40:43], v176 offset:2048
	ds_read_b128 v[44:47], v176 offset:3072
	ds_read_b128 v[48:51], v176 offset:4096
	ds_read_b128 v[52:55], v176 offset:5120
	ds_read_b128 v[56:59], v176 offset:6144
	ds_read_b128 v[60:63], v176 offset:7168
	s_add_u32 s58, s14, 0xb0080
	s_addc_u32 s59, s15, 0
	s_mov_b32 s55, m0
	s_mov_b32 m0, s76
	s_nop 0
	global_load_lds_dwordx4 v170, s[58:59]
	s_mov_b32 m0, s55
	s_nop 0
	s_mov_b32 s55, m0
	s_mov_b32 m0, s77
	s_nop 0
	global_load_lds_dwordx4 v171, s[58:59]
	s_mov_b32 m0, s55
	s_waitcnt vmcnt(8)
	s_waitcnt lgkmcnt(0)
	s_barrier
	s_setprio 1
	s_waitcnt lgkmcnt(1)
	v_mfma_f32_16x16x32_bf16 v[88:91], v[0:3], v[56:59], 0
	v_mfma_f32_16x16x32_bf16 v[64:67], v[0:3], v[32:35], 0
	v_mfma_f32_16x16x32_bf16 v[68:71], v[8:11], v[32:35], 0
	v_mfma_f32_16x16x32_bf16 v[72:75], v[0:3], v[40:43], 0
	v_mfma_f32_16x16x32_bf16 v[76:79], v[8:11], v[40:43], 0
	v_mfma_f32_16x16x32_bf16 v[80:83], v[0:3], v[48:51], 0
	v_mfma_f32_16x16x32_bf16 v[84:87], v[8:11], v[48:51], 0
	s_waitcnt lgkmcnt(0)
	v_mfma_f32_16x16x32_bf16 v[96:99], v[4:7], v[60:63], v[88:91]
	v_mfma_f32_16x16x32_bf16 v[88:91], v[8:11], v[56:59], 0
	v_mfma_f32_16x16x32_bf16 v[64:67], v[4:7], v[36:39], v[64:67]
	v_mfma_f32_16x16x32_bf16 v[68:71], v[12:15], v[36:39], v[68:71]
	v_mfma_f32_16x16x32_bf16 v[72:75], v[4:7], v[44:47], v[72:75]
	v_mfma_f32_16x16x32_bf16 v[76:79], v[12:15], v[44:47], v[76:79]
	v_mfma_f32_16x16x32_bf16 v[80:83], v[4:7], v[52:55], v[80:83]
	v_mfma_f32_16x16x32_bf16 v[84:87], v[12:15], v[52:55], v[84:87]
	v_mfma_f32_16x16x32_bf16 v[100:103], v[12:15], v[60:63], v[88:91]
	s_setprio 0
	s_setprio 1
	v_mfma_f32_16x16x32_bf16 v[88:91], v[16:19], v[32:35], 0
	v_mfma_f32_16x16x32_bf16 v[32:35], v[24:27], v[32:35], 0
	v_mfma_f32_16x16x32_bf16 v[112:115], v[20:23], v[36:39], v[88:91]
	v_mfma_f32_16x16x32_bf16 v[32:35], v[28:31], v[36:39], v[32:35]
	v_mfma_f32_16x16x32_bf16 v[36:39], v[16:19], v[40:43], 0
	v_mfma_f32_16x16x32_bf16 v[40:43], v[24:27], v[40:43], 0
	v_mfma_f32_16x16x32_bf16 v[36:39], v[20:23], v[44:47], v[36:39]
	v_mfma_f32_16x16x32_bf16 v[40:43], v[28:31], v[44:47], v[40:43]
	v_mfma_f32_16x16x32_bf16 v[44:47], v[16:19], v[48:51], 0
	v_mfma_f32_16x16x32_bf16 v[48:51], v[24:27], v[48:51], 0
	v_mfma_f32_16x16x32_bf16 v[44:47], v[20:23], v[52:55], v[44:47]
	v_mfma_f32_16x16x32_bf16 v[48:51], v[28:31], v[52:55], v[48:51]
	v_mfma_f32_16x16x32_bf16 v[52:55], v[16:19], v[56:59], 0
	v_mfma_f32_16x16x32_bf16 v[56:59], v[24:27], v[56:59], 0
	v_mfma_f32_16x16x32_bf16 v[52:55], v[20:23], v[60:63], v[52:55]
	v_mfma_f32_16x16x32_bf16 v[56:59], v[28:31], v[60:63], v[56:59]
	s_setprio 0
	s_barrier
	ds_read_b128 v[60:63], v176 offset:16384
	ds_read_b128 v[88:91], v176 offset:17408
	ds_read_b128 v[92:95], v176 offset:18432
	ds_read_b128 v[104:107], v176 offset:19456
	ds_read_b128 v[108:111], v176 offset:20480
	ds_read_b128 v[116:119], v176 offset:21504
	ds_read_b128 v[120:123], v176 offset:22528
	ds_read_b128 v[124:127], v176 offset:23552
	s_mov_b32 s55, m0
	s_mov_b32 m0, s36
	s_nop 0
	global_load_lds_dwordx4 v168, s[20:21]
	s_mov_b32 m0, s55
	s_nop 0
	s_mov_b32 s55, m0
	s_mov_b32 m0, s39
	s_nop 0
	global_load_lds_dwordx4 v169, s[20:21]
	s_mov_b32 m0, s55
	s_add_u32 s20, s12, 0xb0100
	s_addc_u32 s21, s13, 0
	s_mov_b32 s55, m0
	s_mov_b32 m0, s37
	s_nop 0
	global_load_lds_dwordx4 v168, s[20:21]
	s_mov_b32 m0, s55
	s_nop 0
	s_mov_b32 s55, m0
	s_mov_b32 m0, s40
	s_nop 0
	global_load_lds_dwordx4 v169, s[20:21]
	s_mov_b32 m0, s55
	s_mov_b32 s20, m0
	s_mov_b32 m0, s70
	s_nop 0
	global_load_lds_dwordx4 v170, s[16:17]
	s_mov_b32 m0, s20
	s_nop 0
	s_mov_b32 s20, m0
	s_mov_b32 m0, s71
	s_nop 0
	global_load_lds_dwordx4 v171, s[16:17]
	s_mov_b32 m0, s20
	s_waitcnt vmcnt(8)
	s_waitcnt lgkmcnt(0)
	s_barrier
	s_setprio 1
	s_waitcnt lgkmcnt(7)
	v_mfma_f32_16x16x32_bf16 v[128:131], v[0:3], v[60:63], 0
	s_waitcnt lgkmcnt(6)
	v_mfma_f32_16x16x32_bf16 v[132:135], v[4:7], v[88:91], v[128:131]
	v_mfma_f32_16x16x32_bf16 v[128:131], v[8:11], v[60:63], 0
	v_mfma_f32_16x16x32_bf16 v[136:139], v[12:15], v[88:91], v[128:131]
	s_waitcnt lgkmcnt(5)
	v_mfma_f32_16x16x32_bf16 v[128:131], v[0:3], v[92:95], 0
	s_waitcnt lgkmcnt(4)
	v_mfma_f32_16x16x32_bf16 v[140:143], v[4:7], v[104:107], v[128:131]
	v_mfma_f32_16x16x32_bf16 v[128:131], v[8:11], v[92:95], 0
	v_mfma_f32_16x16x32_bf16 v[144:147], v[12:15], v[104:107], v[128:131]
	s_waitcnt lgkmcnt(3)
	v_mfma_f32_16x16x32_bf16 v[128:131], v[0:3], v[108:111], 0
	s_waitcnt lgkmcnt(1)
	v_mfma_f32_16x16x32_bf16 v[0:3], v[0:3], v[120:123], 0
	v_mfma_f32_16x16x32_bf16 v[148:151], v[4:7], v[116:119], v[128:131]
	s_waitcnt lgkmcnt(0)
	v_mfma_f32_16x16x32_bf16 v[0:3], v[4:7], v[124:127], v[0:3]
	v_mfma_f32_16x16x32_bf16 v[4:7], v[8:11], v[120:123], 0
	v_mfma_f32_16x16x32_bf16 v[128:131], v[8:11], v[108:111], 0
	v_mfma_f32_16x16x32_bf16 v[4:7], v[12:15], v[124:127], v[4:7]
	v_mfma_f32_16x16x32_bf16 v[152:155], v[12:15], v[116:119], v[128:131]
	s_setprio 0
	s_setprio 1
	v_mfma_f32_16x16x32_bf16 v[8:11], v[16:19], v[60:63], 0
	v_mfma_f32_16x16x32_bf16 v[156:159], v[20:23], v[88:91], v[8:11]
	v_mfma_f32_16x16x32_bf16 v[8:11], v[24:27], v[60:63], 0
	v_mfma_f32_16x16x32_bf16 v[160:163], v[28:31], v[88:91], v[8:11]
	v_mfma_f32_16x16x32_bf16 v[8:11], v[16:19], v[92:95], 0
	v_mfma_f32_16x16x32_bf16 v[180:183], v[20:23], v[104:107], v[8:11]
	v_mfma_f32_16x16x32_bf16 v[8:11], v[24:27], v[92:95], 0
	v_mfma_f32_16x16x32_bf16 v[184:187], v[28:31], v[104:107], v[8:11]
	v_mfma_f32_16x16x32_bf16 v[8:11], v[16:19], v[108:111], 0
	v_mfma_f32_16x16x32_bf16 v[188:191], v[20:23], v[116:119], v[8:11]
	v_mfma_f32_16x16x32_bf16 v[8:11], v[24:27], v[108:111], 0
	v_mfma_f32_16x16x32_bf16 v[192:195], v[28:31], v[116:119], v[8:11]
	v_mfma_f32_16x16x32_bf16 v[8:11], v[16:19], v[120:123], 0
	v_mfma_f32_16x16x32_bf16 v[196:199], v[20:23], v[124:127], v[8:11]
	v_mfma_f32_16x16x32_bf16 v[8:11], v[24:27], v[120:123], 0
	v_mfma_f32_16x16x32_bf16 v[200:203], v[28:31], v[124:127], v[8:11]
	s_setprio 0
	s_barrier
	s_nop 4
	ds_read_b128 v[8:11], v177
	ds_read_b128 v[12:15], v177 offset:1024
	ds_read_b128 v[16:19], v177 offset:2048
	ds_read_b128 v[20:23], v177 offset:3072
	ds_read_b128 v[204:207], v178
	ds_read_b128 v[208:211], v178 offset:1024
	ds_read_b128 v[212:215], v178 offset:2048
	ds_read_b128 v[216:219], v178 offset:3072
	ds_read_b128 v[24:27], v176 offset:32768
	ds_read_b128 v[28:31], v176 offset:33792
	ds_read_b128 v[60:63], v176 offset:34816
	ds_read_b128 v[220:223], v176 offset:35840
	ds_read_b128 v[224:227], v176 offset:36864
	ds_read_b128 v[228:231], v176 offset:37888
	ds_read_b128 v[232:235], v176 offset:38912
	ds_read_b128 v[236:239], v176 offset:39936
	s_add_u32 s14, s14, 0xb0100
	s_addc_u32 s15, s15, 0
	s_mov_b32 s20, m0
	s_mov_b32 m0, s72
	s_nop 0
	global_load_lds_dwordx4 v170, s[14:15]
	s_mov_b32 m0, s20
	s_nop 0
	s_mov_b32 s20, m0
	s_mov_b32 m0, s73
	s_nop 0
	global_load_lds_dwordx4 v171, s[14:15]
	s_mov_b32 m0, s20
	s_waitcnt vmcnt(8)
	s_waitcnt lgkmcnt(0)
	s_barrier
	s_setprio 1
	s_waitcnt lgkmcnt(7)
	v_mfma_f32_16x16x32_bf16 v[64:67], v[8:11], v[24:27], v[64:67]
	s_waitcnt lgkmcnt(6)
	v_mfma_f32_16x16x32_bf16 v[120:123], v[12:15], v[28:31], v[64:67]
	v_mfma_f32_16x16x32_bf16 v[64:67], v[16:19], v[24:27], v[68:71]
	v_mfma_f32_16x16x32_bf16 v[116:119], v[20:23], v[28:31], v[64:67]
	s_waitcnt lgkmcnt(5)
	v_mfma_f32_16x16x32_bf16 v[64:67], v[8:11], v[60:63], v[72:75]
	s_waitcnt lgkmcnt(4)
	v_mfma_f32_16x16x32_bf16 v[108:111], v[12:15], v[220:223], v[64:67]
	v_mfma_f32_16x16x32_bf16 v[64:67], v[16:19], v[60:63], v[76:79]
	v_mfma_f32_16x16x32_bf16 v[104:107], v[20:23], v[220:223], v[64:67]
	s_waitcnt lgkmcnt(3)
	v_mfma_f32_16x16x32_bf16 v[64:67], v[8:11], v[224:227], v[80:83]
	s_waitcnt lgkmcnt(2)
	v_mfma_f32_16x16x32_bf16 v[92:95], v[12:15], v[228:231], v[64:67]
	v_mfma_f32_16x16x32_bf16 v[64:67], v[16:19], v[224:227], v[84:87]
	v_mfma_f32_16x16x32_bf16 v[88:91], v[20:23], v[228:231], v[64:67]
	s_waitcnt lgkmcnt(1)
	v_mfma_f32_16x16x32_bf16 v[64:67], v[8:11], v[232:235], v[96:99]
	s_waitcnt lgkmcnt(0)
	v_mfma_f32_16x16x32_bf16 v[76:79], v[12:15], v[236:239], v[64:67]
	v_mfma_f32_16x16x32_bf16 v[64:67], v[16:19], v[232:235], v[100:103]
	v_mfma_f32_16x16x32_bf16 v[72:75], v[20:23], v[236:239], v[64:67]
	s_setprio 0
	s_setprio 1
	v_mfma_f32_16x16x32_bf16 v[64:67], v[204:207], v[24:27], v[112:115]
	v_mfma_f32_16x16x32_bf16 v[24:27], v[212:215], v[24:27], v[32:35]
	v_mfma_f32_16x16x32_bf16 v[124:127], v[216:219], v[28:31], v[24:27]
	v_mfma_f32_16x16x32_bf16 v[24:27], v[204:207], v[60:63], v[36:39]
	v_mfma_f32_16x16x32_bf16 v[100:103], v[208:211], v[220:223], v[24:27]
	v_mfma_f32_16x16x32_bf16 v[24:27], v[212:215], v[60:63], v[40:43]
	v_mfma_f32_16x16x32_bf16 v[96:99], v[216:219], v[220:223], v[24:27]
	v_mfma_f32_16x16x32_bf16 v[24:27], v[204:207], v[224:227], v[44:47]
	v_mfma_f32_16x16x32_bf16 v[84:87], v[208:211], v[228:231], v[24:27]
	v_mfma_f32_16x16x32_bf16 v[24:27], v[212:215], v[224:227], v[48:51]
	v_mfma_f32_16x16x32_bf16 v[80:83], v[216:219], v[228:231], v[24:27]
	v_mfma_f32_16x16x32_bf16 v[24:27], v[204:207], v[232:235], v[52:55]
	v_mfma_f32_16x16x32_bf16 v[60:63], v[208:211], v[236:239], v[24:27]
	v_mfma_f32_16x16x32_bf16 v[24:27], v[212:215], v[232:235], v[56:59]
	v_mfma_f32_16x16x32_bf16 v[128:131], v[208:211], v[28:31], v[64:67]
	v_mfma_f32_16x16x32_bf16 v[56:59], v[216:219], v[236:239], v[24:27]
	s_setprio 0
	s_barrier
	ds_read_b128 v[32:35], v176 offset:49152
	ds_read_b128 v[36:39], v176 offset:50176
	ds_read_b128 v[112:115], v176 offset:51200
	ds_read_b128 v[220:223], v176 offset:52224
	ds_read_b128 v[224:227], v176 offset:53248
	ds_read_b128 v[228:231], v176 offset:54272
	ds_read_b128 v[232:235], v176 offset:55296
	ds_read_b128 v[236:239], v176 offset:56320
	s_add_u32 s14, s12, 0x180
	s_addc_u32 s15, s13, 0
	s_mov_b32 s20, m0
	s_mov_b32 m0, s27
	s_nop 0
	global_load_lds_dwordx4 v168, s[14:15]
	s_mov_b32 m0, s20
	s_nop 0
	s_mov_b32 s20, m0
	s_mov_b32 m0, s28
	s_nop 0
	global_load_lds_dwordx4 v169, s[14:15]
	s_mov_b32 m0, s20
	s_add_u32 s14, s12, 0xb0180
	s_addc_u32 s15, s13, 0
	s_mov_b32 s20, m0
	s_mov_b32 m0, s31
	s_nop 0
	global_load_lds_dwordx4 v168, s[14:15]
	s_mov_b32 m0, s20
	s_nop 0
	s_mov_b32 s20, m0
	s_mov_b32 m0, s33
	s_nop 0
	global_load_lds_dwordx4 v169, s[14:15]
	s_mov_b32 m0, s20
	s_mov_b32 s14, m0
	s_mov_b32 m0, s74
	s_nop 0
	global_load_lds_dwordx4 v170, s[18:19]
	s_mov_b32 m0, s14
	s_nop 0
	s_mov_b32 s14, m0
	s_mov_b32 m0, s75
	s_nop 0
	global_load_lds_dwordx4 v171, s[18:19]
	s_mov_b32 m0, s14
	s_waitcnt vmcnt(8)
	s_waitcnt lgkmcnt(0)
	s_barrier
	s_setprio 1
	s_waitcnt lgkmcnt(7)
	v_mfma_f32_16x16x32_bf16 v[24:27], v[8:11], v[32:35], v[132:135]
	s_waitcnt lgkmcnt(6)
	v_mfma_f32_16x16x32_bf16 v[68:71], v[12:15], v[36:39], v[24:27]
	v_mfma_f32_16x16x32_bf16 v[24:27], v[16:19], v[32:35], v[136:139]
	v_mfma_f32_16x16x32_bf16 v[64:67], v[20:23], v[36:39], v[24:27]
	s_waitcnt lgkmcnt(5)
	v_mfma_f32_16x16x32_bf16 v[24:27], v[8:11], v[112:115], v[140:143]
	s_waitcnt lgkmcnt(4)
	v_mfma_f32_16x16x32_bf16 v[44:47], v[12:15], v[220:223], v[24:27]
	v_mfma_f32_16x16x32_bf16 v[24:27], v[16:19], v[112:115], v[144:147]
	v_mfma_f32_16x16x32_bf16 v[40:43], v[20:23], v[220:223], v[24:27]
	s_waitcnt lgkmcnt(3)
	v_mfma_f32_16x16x32_bf16 v[24:27], v[8:11], v[224:227], v[148:151]
	s_waitcnt lgkmcnt(1)
	v_mfma_f32_16x16x32_bf16 v[0:3], v[8:11], v[232:235], v[0:3]
	v_mfma_f32_16x16x32_bf16 v[28:31], v[12:15], v[228:231], v[24:27]
	v_mfma_f32_16x16x32_bf16 v[24:27], v[16:19], v[224:227], v[152:155]
	s_waitcnt lgkmcnt(0)
	v_mfma_f32_16x16x32_bf16 v[12:15], v[12:15], v[236:239], v[0:3]
	v_mfma_f32_16x16x32_bf16 v[0:3], v[16:19], v[232:235], v[4:7]
	v_mfma_f32_16x16x32_bf16 v[24:27], v[20:23], v[228:231], v[24:27]
	v_mfma_f32_16x16x32_bf16 v[8:11], v[20:23], v[236:239], v[0:3]
	s_setprio 0
	s_setprio 1
	v_mfma_f32_16x16x32_bf16 v[0:3], v[204:207], v[32:35], v[156:159]
	v_mfma_f32_16x16x32_bf16 v[52:55], v[208:211], v[36:39], v[0:3]
	v_mfma_f32_16x16x32_bf16 v[0:3], v[212:215], v[32:35], v[160:163]
	v_mfma_f32_16x16x32_bf16 v[48:51], v[216:219], v[36:39], v[0:3]
	v_mfma_f32_16x16x32_bf16 v[0:3], v[204:207], v[112:115], v[180:183]
	v_mfma_f32_16x16x32_bf16 v[36:39], v[208:211], v[220:223], v[0:3]
	v_mfma_f32_16x16x32_bf16 v[0:3], v[212:215], v[112:115], v[184:187]
	v_mfma_f32_16x16x32_bf16 v[32:35], v[216:219], v[220:223], v[0:3]
	v_mfma_f32_16x16x32_bf16 v[0:3], v[204:207], v[224:227], v[188:191]
	v_mfma_f32_16x16x32_bf16 v[20:23], v[208:211], v[228:231], v[0:3]
	v_mfma_f32_16x16x32_bf16 v[0:3], v[212:215], v[224:227], v[192:195]
	v_mfma_f32_16x16x32_bf16 v[16:19], v[216:219], v[228:231], v[0:3]
	v_mfma_f32_16x16x32_bf16 v[0:3], v[204:207], v[232:235], v[196:199]
	v_mfma_f32_16x16x32_bf16 v[4:7], v[208:211], v[236:239], v[0:3]
	v_mfma_f32_16x16x32_bf16 v[0:3], v[212:215], v[232:235], v[200:203]
	v_mfma_f32_16x16x32_bf16 v[0:3], v[216:219], v[236:239], v[0:3]
	s_setprio 0
	s_barrier
	s_add_u32 s55, s12, 0x200
	s_addc_u32 s57, s13, 0
	s_mov_b32 s58, 0
.LBB0_1373:
	ds_read_b128 v[112:115], v174
	ds_read_b128 v[132:135], v174 offset:1024
	ds_read_b128 v[136:139], v174 offset:2048
	ds_read_b128 v[140:143], v174 offset:3072
	ds_read_b128 v[144:147], v175
	ds_read_b128 v[148:151], v175 offset:1024
	ds_read_b128 v[152:155], v175 offset:2048
	ds_read_b128 v[156:159], v175 offset:3072
	s_add_u32 s12, s16, 0x100
	s_addc_u32 s13, s17, 0
	s_cmp_eq_u32 s58, 40
	s_cselect_b32 s20, s8, s12
	s_cselect_b32 s21, s9, s13
	s_cselect_b32 s18, s10, s55
	s_cselect_b32 s19, s11, s57
	s_add_u32 s14, s20, 0x80
	s_addc_u32 s15, s21, 0
	ds_read_b128 v[160:163], v176
	ds_read_b128 v[180:183], v176 offset:1024
	ds_read_b128 v[184:187], v176 offset:2048
	ds_read_b128 v[188:191], v176 offset:3072
	ds_read_b128 v[192:195], v176 offset:4096
	ds_read_b128 v[196:199], v176 offset:5120
	ds_read_b128 v[200:203], v176 offset:6144
	ds_read_b128 v[204:207], v176 offset:7168
	s_add_u32 s16, s16, 0xb0080
	s_addc_u32 s17, s17, 0
	s_mov_b32 s59, m0
	s_mov_b32 m0, s76
	s_nop 0
	global_load_lds_dwordx4 v170, s[16:17]
	s_mov_b32 m0, s59
	s_nop 0
	s_mov_b32 s59, m0
	s_mov_b32 m0, s77
	s_nop 0
	global_load_lds_dwordx4 v171, s[16:17]
	s_mov_b32 m0, s59
	s_waitcnt vmcnt(8)
	s_waitcnt lgkmcnt(0)
	s_barrier
	s_setprio 1
	s_waitcnt lgkmcnt(7)
	v_mfma_f32_16x16x32_bf16 v[120:123], v[112:115], v[160:163], v[120:123]
	v_mfma_f32_16x16x32_bf16 v[116:119], v[136:139], v[160:163], v[116:119]
	s_waitcnt lgkmcnt(5)
	v_mfma_f32_16x16x32_bf16 v[108:111], v[112:115], v[184:187], v[108:111]
	v_mfma_f32_16x16x32_bf16 v[104:107], v[136:139], v[184:187], v[104:107]
	s_waitcnt lgkmcnt(3)
	v_mfma_f32_16x16x32_bf16 v[92:95], v[112:115], v[192:195], v[92:95]
	v_mfma_f32_16x16x32_bf16 v[88:91], v[136:139], v[192:195], v[88:91]
	s_waitcnt lgkmcnt(1)
	v_mfma_f32_16x16x32_bf16 v[76:79], v[112:115], v[200:203], v[76:79]
	v_mfma_f32_16x16x32_bf16 v[72:75], v[136:139], v[200:203], v[72:75]
	v_mfma_f32_16x16x32_bf16 v[120:123], v[132:135], v[180:183], v[120:123]
	v_mfma_f32_16x16x32_bf16 v[116:119], v[140:143], v[180:183], v[116:119]
	v_mfma_f32_16x16x32_bf16 v[108:111], v[132:135], v[188:191], v[108:111]
	v_mfma_f32_16x16x32_bf16 v[104:107], v[140:143], v[188:191], v[104:107]
	v_mfma_f32_16x16x32_bf16 v[92:95], v[132:135], v[196:199], v[92:95]
	v_mfma_f32_16x16x32_bf16 v[88:91], v[140:143], v[196:199], v[88:91]
	s_waitcnt lgkmcnt(0)
	v_mfma_f32_16x16x32_bf16 v[76:79], v[132:135], v[204:207], v[76:79]
	v_mfma_f32_16x16x32_bf16 v[72:75], v[140:143], v[204:207], v[72:75]
	s_setprio 0
	s_setprio 1
	v_mfma_f32_16x16x32_bf16 v[128:131], v[144:147], v[160:163], v[128:131]
	v_mfma_f32_16x16x32_bf16 v[124:127], v[152:155], v[160:163], v[124:127]
	v_mfma_f32_16x16x32_bf16 v[100:103], v[144:147], v[184:187], v[100:103]
	v_mfma_f32_16x16x32_bf16 v[96:99], v[152:155], v[184:187], v[96:99]
	v_mfma_f32_16x16x32_bf16 v[84:87], v[144:147], v[192:195], v[84:87]
	v_mfma_f32_16x16x32_bf16 v[80:83], v[152:155], v[192:195], v[80:83]
	v_mfma_f32_16x16x32_bf16 v[60:63], v[144:147], v[200:203], v[60:63]
	v_mfma_f32_16x16x32_bf16 v[56:59], v[152:155], v[200:203], v[56:59]
	v_mfma_f32_16x16x32_bf16 v[128:131], v[148:151], v[180:183], v[128:131]
	v_mfma_f32_16x16x32_bf16 v[124:127], v[156:159], v[180:183], v[124:127]
	v_mfma_f32_16x16x32_bf16 v[100:103], v[148:151], v[188:191], v[100:103]
	v_mfma_f32_16x16x32_bf16 v[96:99], v[156:159], v[188:191], v[96:99]
	v_mfma_f32_16x16x32_bf16 v[84:87], v[148:151], v[196:199], v[84:87]
	v_mfma_f32_16x16x32_bf16 v[80:83], v[156:159], v[196:199], v[80:83]
	v_mfma_f32_16x16x32_bf16 v[60:63], v[148:151], v[204:207], v[60:63]
	v_mfma_f32_16x16x32_bf16 v[56:59], v[156:159], v[204:207], v[56:59]
	s_setprio 0
	s_barrier
	ds_read_b128 v[160:163], v176 offset:16384
	ds_read_b128 v[180:183], v176 offset:17408
	ds_read_b128 v[184:187], v176 offset:18432
	ds_read_b128 v[188:191], v176 offset:19456
	ds_read_b128 v[192:195], v176 offset:20480
	ds_read_b128 v[196:199], v176 offset:21504
	ds_read_b128 v[200:203], v176 offset:22528
	ds_read_b128 v[204:207], v176 offset:23552
	s_mov_b32 s16, m0
	s_mov_b32 m0, s36
	s_nop 0
	global_load_lds_dwordx4 v168, s[18:19]
	s_mov_b32 m0, s16
	s_nop 0
	s_mov_b32 s16, m0
	s_mov_b32 m0, s39
	s_nop 0
	global_load_lds_dwordx4 v169, s[18:19]
	s_mov_b32 m0, s16
	s_add_u32 s16, s18, 0xb0000
	s_addc_u32 s17, s19, 0
	s_mov_b32 s59, m0
	s_mov_b32 m0, s37
	s_nop 0
	global_load_lds_dwordx4 v168, s[16:17]
	s_mov_b32 m0, s59
	s_nop 0
	s_mov_b32 s59, m0
	s_mov_b32 m0, s40
	s_nop 0
	global_load_lds_dwordx4 v169, s[16:17]
	s_mov_b32 m0, s59
	s_mov_b32 s16, m0
	s_mov_b32 m0, s70
	s_nop 0
	global_load_lds_dwordx4 v170, s[20:21]
	s_mov_b32 m0, s16
	s_nop 0
	s_mov_b32 s16, m0
	s_mov_b32 m0, s71
	s_nop 0
	global_load_lds_dwordx4 v171, s[20:21]
	s_mov_b32 m0, s16
	s_waitcnt vmcnt(8)
	s_waitcnt lgkmcnt(0)
	s_barrier
	s_setprio 1
	s_waitcnt lgkmcnt(7)
	v_mfma_f32_16x16x32_bf16 v[68:71], v[112:115], v[160:163], v[68:71]
	v_mfma_f32_16x16x32_bf16 v[64:67], v[136:139], v[160:163], v[64:67]
	s_waitcnt lgkmcnt(5)
	v_mfma_f32_16x16x32_bf16 v[44:47], v[112:115], v[184:187], v[44:47]
	v_mfma_f32_16x16x32_bf16 v[40:43], v[136:139], v[184:187], v[40:43]
	s_waitcnt lgkmcnt(3)
	v_mfma_f32_16x16x32_bf16 v[28:31], v[112:115], v[192:195], v[28:31]
	v_mfma_f32_16x16x32_bf16 v[24:27], v[136:139], v[192:195], v[24:27]
	s_waitcnt lgkmcnt(1)
	v_mfma_f32_16x16x32_bf16 v[12:15], v[112:115], v[200:203], v[12:15]
	v_mfma_f32_16x16x32_bf16 v[8:11], v[136:139], v[200:203], v[8:11]
	v_mfma_f32_16x16x32_bf16 v[68:71], v[132:135], v[180:183], v[68:71]
	v_mfma_f32_16x16x32_bf16 v[64:67], v[140:143], v[180:183], v[64:67]
	v_mfma_f32_16x16x32_bf16 v[44:47], v[132:135], v[188:191], v[44:47]
	v_mfma_f32_16x16x32_bf16 v[40:43], v[140:143], v[188:191], v[40:43]
	v_mfma_f32_16x16x32_bf16 v[28:31], v[132:135], v[196:199], v[28:31]
	v_mfma_f32_16x16x32_bf16 v[24:27], v[140:143], v[196:199], v[24:27]
	s_waitcnt lgkmcnt(0)
	v_mfma_f32_16x16x32_bf16 v[12:15], v[132:135], v[204:207], v[12:15]
	v_mfma_f32_16x16x32_bf16 v[8:11], v[140:143], v[204:207], v[8:11]
	s_setprio 0
	s_setprio 1
	v_mfma_f32_16x16x32_bf16 v[52:55], v[144:147], v[160:163], v[52:55]
	v_mfma_f32_16x16x32_bf16 v[48:51], v[152:155], v[160:163], v[48:51]
	v_mfma_f32_16x16x32_bf16 v[36:39], v[144:147], v[184:187], v[36:39]
	v_mfma_f32_16x16x32_bf16 v[32:35], v[152:155], v[184:187], v[32:35]
	v_mfma_f32_16x16x32_bf16 v[20:23], v[144:147], v[192:195], v[20:23]
	v_mfma_f32_16x16x32_bf16 v[16:19], v[152:155], v[192:195], v[16:19]
	v_mfma_f32_16x16x32_bf16 v[4:7], v[144:147], v[200:203], v[4:7]
	v_mfma_f32_16x16x32_bf16 v[0:3], v[152:155], v[200:203], v[0:3]
	v_mfma_f32_16x16x32_bf16 v[52:55], v[148:151], v[180:183], v[52:55]
	v_mfma_f32_16x16x32_bf16 v[48:51], v[156:159], v[180:183], v[48:51]
	v_mfma_f32_16x16x32_bf16 v[36:39], v[148:151], v[188:191], v[36:39]
	v_mfma_f32_16x16x32_bf16 v[32:35], v[156:159], v[188:191], v[32:35]
	v_mfma_f32_16x16x32_bf16 v[20:23], v[148:151], v[196:199], v[20:23]
	v_mfma_f32_16x16x32_bf16 v[16:19], v[156:159], v[196:199], v[16:19]
	v_mfma_f32_16x16x32_bf16 v[4:7], v[148:151], v[204:207], v[4:7]
	v_mfma_f32_16x16x32_bf16 v[0:3], v[156:159], v[204:207], v[0:3]
	s_setprio 0
	s_barrier
	ds_read_b128 v[112:115], v177
	ds_read_b128 v[132:135], v177 offset:1024
	ds_read_b128 v[136:139], v177 offset:2048
	ds_read_b128 v[140:143], v177 offset:3072
	ds_read_b128 v[144:147], v178
	ds_read_b128 v[148:151], v178 offset:1024
	ds_read_b128 v[152:155], v178 offset:2048
	ds_read_b128 v[156:159], v178 offset:3072
	ds_read_b128 v[160:163], v176 offset:32768
	ds_read_b128 v[180:183], v176 offset:33792
	ds_read_b128 v[184:187], v176 offset:34816
	ds_read_b128 v[188:191], v176 offset:35840
	ds_read_b128 v[192:195], v176 offset:36864
	ds_read_b128 v[196:199], v176 offset:37888
	ds_read_b128 v[200:203], v176 offset:38912
	ds_read_b128 v[204:207], v176 offset:39936
	s_add_u32 s16, s20, 0xb0000
	s_addc_u32 s17, s21, 0
	s_mov_b32 s20, m0
	s_mov_b32 m0, s72
	s_nop 0
	global_load_lds_dwordx4 v170, s[16:17]
	s_mov_b32 m0, s20
	s_nop 0
	s_mov_b32 s20, m0
	s_mov_b32 m0, s73
	s_nop 0
	global_load_lds_dwordx4 v171, s[16:17]
	s_mov_b32 m0, s20
	s_waitcnt vmcnt(8)
	s_waitcnt lgkmcnt(0)
	s_barrier
	s_setprio 1
	s_waitcnt lgkmcnt(7)
	v_mfma_f32_16x16x32_bf16 v[120:123], v[112:115], v[160:163], v[120:123]
	v_mfma_f32_16x16x32_bf16 v[116:119], v[136:139], v[160:163], v[116:119]
	s_waitcnt lgkmcnt(5)
	v_mfma_f32_16x16x32_bf16 v[108:111], v[112:115], v[184:187], v[108:111]
	v_mfma_f32_16x16x32_bf16 v[104:107], v[136:139], v[184:187], v[104:107]
	s_waitcnt lgkmcnt(3)
	v_mfma_f32_16x16x32_bf16 v[92:95], v[112:115], v[192:195], v[92:95]
	v_mfma_f32_16x16x32_bf16 v[88:91], v[136:139], v[192:195], v[88:91]
	s_waitcnt lgkmcnt(1)
	v_mfma_f32_16x16x32_bf16 v[76:79], v[112:115], v[200:203], v[76:79]
	v_mfma_f32_16x16x32_bf16 v[72:75], v[136:139], v[200:203], v[72:75]
	v_mfma_f32_16x16x32_bf16 v[120:123], v[132:135], v[180:183], v[120:123]
	v_mfma_f32_16x16x32_bf16 v[116:119], v[140:143], v[180:183], v[116:119]
	v_mfma_f32_16x16x32_bf16 v[108:111], v[132:135], v[188:191], v[108:111]
	v_mfma_f32_16x16x32_bf16 v[104:107], v[140:143], v[188:191], v[104:107]
	v_mfma_f32_16x16x32_bf16 v[92:95], v[132:135], v[196:199], v[92:95]
	v_mfma_f32_16x16x32_bf16 v[88:91], v[140:143], v[196:199], v[88:91]
	s_waitcnt lgkmcnt(0)
	v_mfma_f32_16x16x32_bf16 v[76:79], v[132:135], v[204:207], v[76:79]
	v_mfma_f32_16x16x32_bf16 v[72:75], v[140:143], v[204:207], v[72:75]
	s_setprio 0
	s_setprio 1
	v_mfma_f32_16x16x32_bf16 v[128:131], v[144:147], v[160:163], v[128:131]
	v_mfma_f32_16x16x32_bf16 v[124:127], v[152:155], v[160:163], v[124:127]
	v_mfma_f32_16x16x32_bf16 v[100:103], v[144:147], v[184:187], v[100:103]
	v_mfma_f32_16x16x32_bf16 v[96:99], v[152:155], v[184:187], v[96:99]
	v_mfma_f32_16x16x32_bf16 v[84:87], v[144:147], v[192:195], v[84:87]
	v_mfma_f32_16x16x32_bf16 v[80:83], v[152:155], v[192:195], v[80:83]
	v_mfma_f32_16x16x32_bf16 v[60:63], v[144:147], v[200:203], v[60:63]
	v_mfma_f32_16x16x32_bf16 v[56:59], v[152:155], v[200:203], v[56:59]
	v_mfma_f32_16x16x32_bf16 v[128:131], v[148:151], v[180:183], v[128:131]
	v_mfma_f32_16x16x32_bf16 v[124:127], v[156:159], v[180:183], v[124:127]
	v_mfma_f32_16x16x32_bf16 v[100:103], v[148:151], v[188:191], v[100:103]
	v_mfma_f32_16x16x32_bf16 v[96:99], v[156:159], v[188:191], v[96:99]
	v_mfma_f32_16x16x32_bf16 v[84:87], v[148:151], v[196:199], v[84:87]
	v_mfma_f32_16x16x32_bf16 v[80:83], v[156:159], v[196:199], v[80:83]
	v_mfma_f32_16x16x32_bf16 v[60:63], v[148:151], v[204:207], v[60:63]
	v_mfma_f32_16x16x32_bf16 v[56:59], v[156:159], v[204:207], v[56:59]
	s_setprio 0
	s_barrier
	ds_read_b128 v[160:163], v176 offset:49152
	ds_read_b128 v[180:183], v176 offset:50176
	ds_read_b128 v[184:187], v176 offset:51200
	ds_read_b128 v[188:191], v176 offset:52224
	ds_read_b128 v[192:195], v176 offset:53248
	ds_read_b128 v[196:199], v176 offset:54272
	ds_read_b128 v[200:203], v176 offset:55296
	ds_read_b128 v[204:207], v176 offset:56320
	s_add_u32 s16, s18, 0x80
	s_addc_u32 s17, s19, 0
	s_mov_b32 s20, m0
	s_mov_b32 m0, s27
	s_nop 0
	global_load_lds_dwordx4 v168, s[16:17]
	s_mov_b32 m0, s20
	s_nop 0
	s_mov_b32 s20, m0
	s_mov_b32 m0, s28
	s_nop 0
	global_load_lds_dwordx4 v169, s[16:17]
	s_mov_b32 m0, s20
	s_add_u32 s16, s18, 0xb0080
	s_addc_u32 s17, s19, 0
	s_mov_b32 s18, m0
	s_mov_b32 m0, s31
	s_nop 0
	global_load_lds_dwordx4 v168, s[16:17]
	s_mov_b32 m0, s18
	s_nop 0
	s_mov_b32 s18, m0
	s_mov_b32 m0, s33
	s_nop 0
	global_load_lds_dwordx4 v169, s[16:17]
	s_mov_b32 m0, s18
	s_mov_b32 s16, m0
	s_mov_b32 m0, s74
	s_nop 0
	global_load_lds_dwordx4 v170, s[14:15]
	s_mov_b32 m0, s16
	s_nop 0
	s_mov_b32 s16, m0
	s_mov_b32 m0, s75
	s_nop 0
	global_load_lds_dwordx4 v171, s[14:15]
	s_mov_b32 m0, s16
	s_waitcnt vmcnt(8)
	s_waitcnt lgkmcnt(0)
	s_barrier
	s_setprio 1
	s_waitcnt lgkmcnt(7)
	v_mfma_f32_16x16x32_bf16 v[68:71], v[112:115], v[160:163], v[68:71]
	v_mfma_f32_16x16x32_bf16 v[64:67], v[136:139], v[160:163], v[64:67]
	s_waitcnt lgkmcnt(5)
	v_mfma_f32_16x16x32_bf16 v[44:47], v[112:115], v[184:187], v[44:47]
	v_mfma_f32_16x16x32_bf16 v[40:43], v[136:139], v[184:187], v[40:43]
	s_waitcnt lgkmcnt(3)
	v_mfma_f32_16x16x32_bf16 v[28:31], v[112:115], v[192:195], v[28:31]
	v_mfma_f32_16x16x32_bf16 v[24:27], v[136:139], v[192:195], v[24:27]
	s_waitcnt lgkmcnt(1)
	v_mfma_f32_16x16x32_bf16 v[12:15], v[112:115], v[200:203], v[12:15]
	v_mfma_f32_16x16x32_bf16 v[8:11], v[136:139], v[200:203], v[8:11]
	v_mfma_f32_16x16x32_bf16 v[68:71], v[132:135], v[180:183], v[68:71]
	v_mfma_f32_16x16x32_bf16 v[64:67], v[140:143], v[180:183], v[64:67]
	v_mfma_f32_16x16x32_bf16 v[44:47], v[132:135], v[188:191], v[44:47]
	v_mfma_f32_16x16x32_bf16 v[40:43], v[140:143], v[188:191], v[40:43]
	v_mfma_f32_16x16x32_bf16 v[28:31], v[132:135], v[196:199], v[28:31]
	v_mfma_f32_16x16x32_bf16 v[24:27], v[140:143], v[196:199], v[24:27]
	s_waitcnt lgkmcnt(0)
	v_mfma_f32_16x16x32_bf16 v[12:15], v[132:135], v[204:207], v[12:15]
	v_mfma_f32_16x16x32_bf16 v[8:11], v[140:143], v[204:207], v[8:11]
	s_setprio 0
	s_setprio 1
	v_mfma_f32_16x16x32_bf16 v[52:55], v[144:147], v[160:163], v[52:55]
	v_mfma_f32_16x16x32_bf16 v[48:51], v[152:155], v[160:163], v[48:51]
	v_mfma_f32_16x16x32_bf16 v[36:39], v[144:147], v[184:187], v[36:39]
	v_mfma_f32_16x16x32_bf16 v[32:35], v[152:155], v[184:187], v[32:35]
	v_mfma_f32_16x16x32_bf16 v[20:23], v[144:147], v[192:195], v[20:23]
	v_mfma_f32_16x16x32_bf16 v[16:19], v[152:155], v[192:195], v[16:19]
	v_mfma_f32_16x16x32_bf16 v[4:7], v[144:147], v[200:203], v[4:7]
	v_mfma_f32_16x16x32_bf16 v[0:3], v[152:155], v[200:203], v[0:3]
	v_mfma_f32_16x16x32_bf16 v[52:55], v[148:151], v[180:183], v[52:55]
	v_mfma_f32_16x16x32_bf16 v[48:51], v[156:159], v[180:183], v[48:51]
	v_mfma_f32_16x16x32_bf16 v[36:39], v[148:151], v[188:191], v[36:39]
	v_mfma_f32_16x16x32_bf16 v[32:35], v[156:159], v[188:191], v[32:35]
	v_mfma_f32_16x16x32_bf16 v[20:23], v[148:151], v[196:199], v[20:23]
	v_mfma_f32_16x16x32_bf16 v[16:19], v[156:159], v[196:199], v[16:19]
	v_mfma_f32_16x16x32_bf16 v[4:7], v[148:151], v[204:207], v[4:7]
	v_mfma_f32_16x16x32_bf16 v[0:3], v[156:159], v[204:207], v[0:3]
	s_setprio 0
	s_barrier
	s_add_i32 s58, s58, 2
	s_add_u32 s55, s55, 0x100
	s_addc_u32 s57, s57, 0
	s_cmp_gt_u32 s58, 41
	s_mov_b64 s[16:17], s[12:13]
	s_cbranch_scc0 .LBB0_1373
	s_and_b64 vcc, exec, s[6:7]
	s_cbranch_vccz .LBB0_1376
	s_barrier
